# stack: pipelined scan + batched readout0 epilogue + attention loop without per-tile NM copies and with counted lgkmcnt waits
# speedup vs baseline: 1.0015x; 1.0015x over previous
.LBB0_1125:
	s_waitcnt lgkmcnt(3)
	v_mfma_f32_32x32x16_bf16 v[112:127], v[100:103], v[128:131], v[80:95]
	s_add_i32 s39, s39, 0x8000
	s_add_i32 s37, s37, 1
	v_add_f32_e32 v177, v169, v168
	v_lshl_add_u64 v[202:203], v[202:203], 0, s[84:85]
	v_lshl_add_u64 v[204:205], v[204:205], 0, s[72:73]
	s_cmp_eq_u32 s39, 0x228000
	s_waitcnt lgkmcnt(2)
	v_mfma_f32_32x32x16_bf16 v[112:127], v[96:99], v[132:135], v[112:127]
	s_waitcnt lgkmcnt(1)
	v_mfma_f32_32x32x16_bf16 v[112:127], v[104:107], v[136:139], v[112:127]
	s_waitcnt lgkmcnt(0)
	v_mfma_f32_32x32x16_bf16 v[112:127], v[108:111], v[140:143], v[112:127]
	s_cbranch_scc1 .LBB0_1139

.LBB0_1128:
	s_waitcnt lgkmcnt(11)
	v_mfma_f32_32x32x16_bf16 v[96:111], v[64:67], v[128:131], v[80:95]
	v_exp_f32_e32 v210, v112
	v_exp_f32_e32 v212, v113
	v_exp_f32_e32 v214, v114
	v_exp_f32_e32 v216, v115
	v_exp_f32_e32 v211, v120
	v_exp_f32_e32 v213, v121
	v_exp_f32_e32 v215, v122
	s_waitcnt lgkmcnt(10)
	v_mfma_f32_32x32x16_bf16 v[96:111], v[68:71], v[132:135], v[96:111]
	v_exp_f32_e32 v217, v123
	v_exp_f32_e32 v220, v116
	v_exp_f32_e32 v222, v117
	v_exp_f32_e32 v224, v118
	v_exp_f32_e32 v226, v119
	v_exp_f32_e32 v221, v124
	v_exp_f32_e32 v223, v125
	s_waitcnt lgkmcnt(9)
	v_mfma_f32_32x32x16_bf16 v[96:111], v[72:75], v[136:139], v[96:111]
	v_exp_f32_e32 v225, v126
	v_exp_f32_e32 v227, v127
	v_pk_add_f32 v[64:65], v[210:211], v[212:213]
	v_pk_add_f32 v[66:67], v[214:215], v[216:217]
	v_sub_f32_e32 v219, v201, v201
	v_pk_add_f32 v[64:65], v[64:65], v[66:67]
	v_pk_add_f32 v[66:67], v[220:221], v[222:223]
	s_waitcnt lgkmcnt(8)
	v_mfma_f32_32x32x16_bf16 v[96:111], v[76:79], v[140:143], v[96:111]
	v_add_f32_e64 v68, v224, v226
	v_add_f32_e64 v69, v225, v227
	v_cmp_neq_f32_e64 s[0:1], 0, v219
	v_add_f32_e64 v66, v66, v68
	v_add_f32_e64 v67, v67, v69
	v_pk_add_f32 v[64:65], v[64:65], v[66:67]
	s_nop 0
	v_add_f32_e32 v218, v64, v65
	v_cmp_nge_f32_e32 vcc, s97, v218
	s_or_b64 vcc, s[0:1], vcc
	s_cbranch_vccz .LBB0_1130
	v_max_f32_e32 v64, v113, v113
	v_max_f32_e32 v65, v112, v112
	v_max_f32_e32 v64, v65, v64
	v_max_f32_e32 v65, v115, v115
	v_max_f32_e32 v66, v114, v114
	v_max_f32_e32 v65, v66, v65
	v_max_f32_e32 v66, v119, v119
	v_max_f32_e32 v67, v118, v118
	v_max_f32_e32 v66, v67, v66
	v_max3_f32 v66, v116, v117, v66
	v_max3_f32 v64, v64, v65, v66
	v_max_f32_e32 v65, v123, v123
	v_max_f32_e32 v66, v122, v122
	v_max_f32_e32 v65, v66, v65
	v_max_f32_e32 v66, v127, v127
	v_max_f32_e32 v67, v126, v126
	v_max_f32_e32 v66, v67, v66
	v_max3_f32 v65, v120, v121, v65
	v_max3_f32 v66, v124, v125, v66
	v_max3_f32 v64, v64, v65, v66
	v_add_f32_e32 v64, v219, v64
	ds_bpermute_b32 v65, v244, v64
	s_waitcnt lgkmcnt(0)
	v_max3_f32 v67, v64, v65, 0
	v_sub_f32_e32 v64, v67, v219
	v_sub_f32_e32 v65, v112, v64
	v_exp_f32_e32 v210, v65
	v_sub_f32_e32 v65, v113, v64
	v_exp_f32_e32 v212, v65
	v_sub_f32_e32 v65, v114, v64
	v_exp_f32_e32 v214, v65
	v_sub_f32_e32 v65, v115, v64
	v_exp_f32_e32 v216, v65
	v_sub_f32_e32 v65, v116, v64
	v_exp_f32_e32 v211, v65
	v_sub_f32_e32 v65, v117, v64
	v_exp_f32_e32 v213, v65
	v_sub_f32_e32 v65, v118, v64
	v_exp_f32_e32 v215, v65
	v_sub_f32_e32 v65, v120, v64
	v_exp_f32_e32 v112, v65
	v_sub_f32_e32 v65, v121, v64
	v_exp_f32_e32 v114, v65
	v_sub_f32_e32 v65, v122, v64
	v_exp_f32_e32 v113, v65
	v_sub_f32_e32 v65, v123, v64
	v_exp_f32_e32 v115, v65
	v_sub_f32_e32 v65, v124, v64
	v_exp_f32_e32 v116, v65
	v_sub_f32_e32 v65, v125, v64
	v_exp_f32_e32 v120, v65
	v_sub_f32_e32 v65, v126, v64
	v_exp_f32_e32 v117, v65
	v_sub_f32_e32 v65, v127, v64
	v_exp_f32_e32 v121, v65
	v_sub_f32_e32 v64, v119, v64
	v_exp_f32_e64 v66, -v67
	v_exp_f32_e32 v217, v64
	v_pk_add_f32 v[64:65], v[112:113], v[114:115]
	v_pk_add_f32 v[68:69], v[116:117], v[120:121]
	v_pk_add_f32 v[64:65], v[64:65], v[64:65] op_sel:[0,1] op_sel_hi:[1,0]
	v_pk_add_f32 v[68:69], v[68:69], v[68:69] op_sel:[0,1] op_sel_hi:[1,0]
	v_mov_b32_e32 v65, v201
	v_mov_b32_e32 v69, v67
	v_mul_f32_e32 v177, v177, v66
	v_pk_add_f32 v[80:81], v[64:65], v[68:69]
	v_pk_mul_f32 v[62:63], v[62:63], v[66:67] op_sel_hi:[1,0]
	v_pk_mul_f32 v[60:61], v[60:61], v[66:67] op_sel_hi:[1,0]
	v_pk_mul_f32 v[58:59], v[58:59], v[66:67] op_sel_hi:[1,0]
	v_pk_mul_f32 v[56:57], v[56:57], v[66:67] op_sel_hi:[1,0]
	v_pk_mul_f32 v[54:55], v[54:55], v[66:67] op_sel_hi:[1,0]
	v_pk_mul_f32 v[52:53], v[52:53], v[66:67] op_sel_hi:[1,0]
	v_pk_mul_f32 v[50:51], v[50:51], v[66:67] op_sel_hi:[1,0]
	v_pk_mul_f32 v[48:49], v[48:49], v[66:67] op_sel_hi:[1,0]
	v_pk_mul_f32 v[46:47], v[46:47], v[66:67] op_sel_hi:[1,0]
	v_pk_mul_f32 v[44:45], v[44:45], v[66:67] op_sel_hi:[1,0]
	v_pk_mul_f32 v[42:43], v[42:43], v[66:67] op_sel_hi:[1,0]
	v_pk_mul_f32 v[40:41], v[40:41], v[66:67] op_sel_hi:[1,0]
	v_pk_mul_f32 v[38:39], v[38:39], v[66:67] op_sel_hi:[1,0]
	v_pk_mul_f32 v[36:37], v[36:37], v[66:67] op_sel_hi:[1,0]
	v_pk_mul_f32 v[34:35], v[34:35], v[66:67] op_sel_hi:[1,0]
	v_pk_mul_f32 v[32:33], v[32:33], v[66:67] op_sel_hi:[1,0]
	v_pk_mul_f32 v[30:31], v[30:31], v[66:67] op_sel_hi:[1,0]
	v_pk_mul_f32 v[28:29], v[28:29], v[66:67] op_sel_hi:[1,0]
	v_pk_mul_f32 v[26:27], v[26:27], v[66:67] op_sel_hi:[1,0]
	v_pk_mul_f32 v[24:25], v[24:25], v[66:67] op_sel_hi:[1,0]
	v_pk_mul_f32 v[22:23], v[22:23], v[66:67] op_sel_hi:[1,0]
	v_pk_mul_f32 v[20:21], v[20:21], v[66:67] op_sel_hi:[1,0]
	v_pk_mul_f32 v[18:19], v[18:19], v[66:67] op_sel_hi:[1,0]
	v_pk_mul_f32 v[16:17], v[16:17], v[66:67] op_sel_hi:[1,0]
	v_pk_mul_f32 v[14:15], v[14:15], v[66:67] op_sel_hi:[1,0]
	v_pk_mul_f32 v[12:13], v[12:13], v[66:67] op_sel_hi:[1,0]
	v_pk_mul_f32 v[10:11], v[10:11], v[66:67] op_sel_hi:[1,0]
	v_pk_mul_f32 v[8:9], v[8:9], v[66:67] op_sel_hi:[1,0]
	v_pk_mul_f32 v[6:7], v[6:7], v[66:67] op_sel_hi:[1,0]
	v_pk_mul_f32 v[4:5], v[4:5], v[66:67] op_sel_hi:[1,0]
	v_pk_mul_f32 v[2:3], v[2:3], v[66:67] op_sel_hi:[1,0]
	v_pk_mul_f32 v[0:1], v[0:1], v[66:67] op_sel_hi:[1,0]
	v_pk_add_f32 v[66:67], v[214:215], v[216:217]
	v_pk_add_f32 v[68:69], v[210:211], v[212:213]
	v_xor_b32_e32 v64, 0x80000000, v81
	v_pk_add_f32 v[66:67], v[68:69], v[66:67]
	v_mov_b32_e32 v65, v64
	v_pk_add_f32 v[66:67], v[66:67], v[66:67] op_sel:[0,1] op_sel_hi:[1,0]
	v_mov_b32_e32 v68, v64
	v_mov_b32_e32 v67, v201
	v_pk_add_f32 v[218:219], v[66:67], v[80:81] neg_lo:[0,1] neg_hi:[0,1]
	v_mov_b32_e32 v67, v64
	v_add_f32_e32 v218, v66, v80
	v_mov_b32_e32 v66, v64
	v_mov_b32_e32 v69, v64
	v_mov_b32_e32 v70, v64
	v_mov_b32_e32 v71, v64
	v_mov_b32_e32 v72, v64
	v_mov_b32_e32 v73, v64
	v_mov_b32_e32 v74, v64
	v_mov_b32_e32 v75, v64
	v_mov_b32_e32 v76, v64
	v_mov_b32_e32 v77, v64
	v_mov_b32_e32 v78, v64
	v_mov_b32_e32 v79, v64
	v_mov_b32_e32 v201, v81
	v_mov_b32_e32 v80, v64
	v_mov_b32_e32 v81, v64
	v_mov_b32_e32 v82, v64
	v_mov_b32_e32 v83, v64
	v_mov_b32_e32 v84, v64
	v_mov_b32_e32 v85, v64
	v_mov_b32_e32 v86, v64
	v_mov_b32_e32 v87, v64
	v_mov_b32_e32 v88, v64
	v_mov_b32_e32 v89, v64
	v_mov_b32_e32 v90, v64
	v_mov_b32_e32 v91, v64
	v_mov_b32_e32 v92, v64
	v_mov_b32_e32 v93, v64
	v_mov_b32_e32 v94, v64
	v_mov_b32_e32 v95, v64
	v_mov_b32_e32 v220, v211
	v_mov_b32_e32 v222, v213
	v_mov_b32_e32 v224, v215
	v_mov_b32_e32 v226, v217
	v_mov_b32_e32 v211, v112
	v_mov_b32_e32 v213, v114
	v_mov_b32_e32 v215, v113
	v_mov_b32_e32 v217, v115
	v_mov_b32_e32 v221, v116
	v_mov_b32_e32 v223, v120
	v_mov_b32_e32 v225, v117
	v_mov_b32_e32 v227, v121
	s_branch .LBB0_1131
.LBB0_1130:
.LBB0_1131:
	v_cvt_pk_bf16_f32 v112, v210, v212
	v_cvt_pk_bf16_f32 v113, v214, v216
	v_cvt_pk_bf16_f32 v114, v220, v222
	v_cvt_pk_bf16_f32 v115, v224, v226
	v_cvt_pk_bf16_f32 v116, v211, v213
	v_cvt_pk_bf16_f32 v117, v215, v217
	s_waitcnt lgkmcnt(0)
	v_mfma_f32_32x32x16_bf16 v[32:47], v[144:147], v[112:115], v[32:47]
	v_cvt_pk_bf16_f32 v118, v221, v223
	v_cvt_pk_bf16_f32 v119, v225, v227
	v_exp_f32_e32 v210, v97
	v_exp_f32_e32 v212, v98
	v_exp_f32_e32 v214, v99
	v_exp_f32_e32 v211, v101
	v_exp_f32_e32 v213, v102
	v_mfma_f32_32x32x16_bf16 v[16:31], v[148:151], v[112:115], v[16:31]
	v_exp_f32_e32 v215, v103
	v_cmp_neq_f32_e64 s[0:1], 0, v219
	v_mfma_f32_32x32x16_bf16 v[48:63], v[172:175], v[112:115], v[48:63]
	v_exp_f32_e32 v174, v96
	v_exp_f32_e32 v175, v100
	v_mfma_f32_32x32x16_bf16 v[0:15], v[152:155], v[112:115], v[0:15]
	v_add_u32_e32 v112, v250, v241
	v_mfma_f32_32x32x16_bf16 v[32:47], v[160:163], v[116:119], v[32:47]
	v_exp_f32_e32 v160, v104
	v_exp_f32_e32 v162, v105
	v_exp_f32_e32 v161, v108
	v_exp_f32_e32 v163, v109
	v_mfma_f32_32x32x16_bf16 v[16:31], v[164:167], v[116:119], v[16:31]
	v_exp_f32_e32 v164, v106
	v_exp_f32_e32 v166, v107
	v_exp_f32_e32 v165, v110
	v_exp_f32_e32 v167, v111
	s_nop 0
	v_pk_add_f32 v[172:173], v[164:165], v[166:167]
	v_mfma_f32_32x32x16_bf16 v[48:63], v[156:159], v[116:119], v[48:63]
	ds_read_b128 v[156:159], v112 offset:16384
	ds_read_b128 v[152:155], v112 offset:20480
	ds_read_b128 v[148:151], v112 offset:24576
	ds_read_b128 v[144:147], v112 offset:28672
	v_add_u32_e32 v112, v250, v242
	v_mfma_f32_32x32x16_bf16 v[0:15], v[168:171], v[116:119], v[0:15]
	v_add_f32_e64 v168, v174, v210
	v_add_f32_e64 v169, v175, v211
	v_add_f32_e64 v170, v212, v214
	v_add_f32_e64 v171, v213, v215
	ds_read_b128 v[124:127], v112 offset:16384
	ds_read_b128 v[120:123], v112 offset:20480
	ds_read_b128 v[116:119], v112 offset:24576
	ds_read_b128 v[112:115], v112 offset:28672
	v_pk_add_f32 v[168:169], v[168:169], v[170:171]
	v_pk_add_f32 v[170:171], v[160:161], v[162:163]
	v_pk_add_f32 v[168:169], v[168:169], v[168:169] op_sel:[0,1] op_sel_hi:[1,0]
	v_pk_add_f32 v[170:171], v[170:171], v[172:173]
	v_mov_b32_e32 v169, v177
	v_pk_add_f32 v[170:171], v[170:171], v[170:171] op_sel:[0,1] op_sel_hi:[1,0]
	s_nop 0
	v_mov_b32_e32 v171, v218
	v_pk_add_f32 v[168:169], v[168:169], v[170:171]
	s_nop 0
	v_cmp_nge_f32_e32 vcc, s97, v168
	s_or_b64 vcc, vcc, s[0:1]
	s_cbranch_vccz .LBB0_1133
	v_max_f32_e32 v64, v97, v97
	v_max_f32_e32 v65, v96, v96
	v_max_f32_e32 v64, v65, v64
	v_max_f32_e32 v65, v99, v99
	v_max_f32_e32 v66, v98, v98
	v_max_f32_e32 v65, v66, v65
	v_max_f32_e32 v66, v103, v103
	v_max_f32_e32 v67, v102, v102
	v_max_f32_e32 v66, v67, v66
	v_max3_f32 v66, v100, v101, v66
	v_max3_f32 v64, v64, v65, v66
	v_max_f32_e32 v65, v107, v107
	v_max_f32_e32 v66, v106, v106
	v_max_f32_e32 v65, v66, v65
	v_max_f32_e32 v66, v111, v111
	v_max_f32_e32 v67, v110, v110
	v_max_f32_e32 v66, v67, v66
	v_max3_f32 v65, v104, v105, v65
	v_max3_f32 v66, v108, v109, v66
	v_max3_f32 v64, v64, v65, v66
	v_add_f32_e32 v64, v64, v219
	ds_bpermute_b32 v65, v244, v64
	s_waitcnt lgkmcnt(0)
	v_max3_f32 v64, v64, v65, 0
	v_sub_f32_e32 v67, v64, v219
	v_sub_f32_e32 v68, v96, v67
	v_exp_f32_e32 v96, v68
	v_sub_f32_e32 v68, v97, v67
	v_exp_f32_e32 v170, v68
	v_sub_f32_e32 v68, v98, v67
	v_exp_f32_e32 v98, v68
	v_sub_f32_e32 v68, v99, v67
	v_exp_f32_e32 v172, v68
	v_sub_f32_e32 v68, v100, v67
	v_exp_f32_e32 v160, v68
	v_sub_f32_e32 v68, v101, v67
	v_exp_f32_e32 v162, v68
	v_sub_f32_e32 v68, v102, v67
	v_exp_f32_e32 v164, v68
	v_sub_f32_e32 v68, v103, v67
	v_exp_f32_e32 v166, v68
	v_sub_f32_e32 v68, v104, v67
	v_exp_f32_e32 v97, v68
	v_sub_f32_e32 v68, v105, v67
	v_exp_f32_e32 v171, v68
	v_sub_f32_e32 v68, v106, v67
	v_exp_f32_e32 v99, v68
	v_sub_f32_e32 v68, v107, v67
	v_exp_f32_e32 v173, v68
	v_sub_f32_e32 v68, v108, v67
	v_exp_f32_e32 v161, v68
	v_sub_f32_e32 v68, v109, v67
	v_exp_f32_e32 v163, v68
	v_sub_f32_e32 v68, v110, v67
	v_sub_f32_e32 v67, v111, v67
	v_exp_f32_e32 v165, v68
	v_exp_f32_e32 v167, v67
	v_exp_f32_e64 v66, -v64
	v_pk_add_f32 v[68:69], v[160:161], v[162:163]
	v_add_f32_e32 v201, v201, v64
	v_pk_add_f32 v[70:71], v[164:165], v[166:167]
	v_mul_f32_e32 v65, v169, v66
	v_pk_mul_f32 v[62:63], v[62:63], v[66:67] op_sel_hi:[1,0]
	v_pk_mul_f32 v[60:61], v[60:61], v[66:67] op_sel_hi:[1,0]
	v_pk_mul_f32 v[58:59], v[58:59], v[66:67] op_sel_hi:[1,0]
	v_pk_mul_f32 v[56:57], v[56:57], v[66:67] op_sel_hi:[1,0]
	v_pk_mul_f32 v[54:55], v[54:55], v[66:67] op_sel_hi:[1,0]
	v_pk_mul_f32 v[52:53], v[52:53], v[66:67] op_sel_hi:[1,0]
	v_pk_mul_f32 v[50:51], v[50:51], v[66:67] op_sel_hi:[1,0]
	v_pk_mul_f32 v[48:49], v[48:49], v[66:67] op_sel_hi:[1,0]
	v_pk_mul_f32 v[46:47], v[46:47], v[66:67] op_sel_hi:[1,0]
	v_pk_mul_f32 v[44:45], v[44:45], v[66:67] op_sel_hi:[1,0]
	v_pk_mul_f32 v[42:43], v[42:43], v[66:67] op_sel_hi:[1,0]
	v_pk_mul_f32 v[40:41], v[40:41], v[66:67] op_sel_hi:[1,0]
	v_pk_mul_f32 v[38:39], v[38:39], v[66:67] op_sel_hi:[1,0]
	v_pk_mul_f32 v[36:37], v[36:37], v[66:67] op_sel_hi:[1,0]
	v_pk_mul_f32 v[34:35], v[34:35], v[66:67] op_sel_hi:[1,0]
	v_pk_mul_f32 v[32:33], v[32:33], v[66:67] op_sel_hi:[1,0]
	v_pk_mul_f32 v[30:31], v[30:31], v[66:67] op_sel_hi:[1,0]
	v_pk_mul_f32 v[28:29], v[28:29], v[66:67] op_sel_hi:[1,0]
	v_pk_mul_f32 v[26:27], v[26:27], v[66:67] op_sel_hi:[1,0]
	v_pk_mul_f32 v[24:25], v[24:25], v[66:67] op_sel_hi:[1,0]
	v_pk_mul_f32 v[22:23], v[22:23], v[66:67] op_sel_hi:[1,0]
	v_pk_mul_f32 v[20:21], v[20:21], v[66:67] op_sel_hi:[1,0]
	v_pk_mul_f32 v[18:19], v[18:19], v[66:67] op_sel_hi:[1,0]
	v_pk_mul_f32 v[16:17], v[16:17], v[66:67] op_sel_hi:[1,0]
	v_pk_mul_f32 v[14:15], v[14:15], v[66:67] op_sel_hi:[1,0]
	v_pk_mul_f32 v[12:13], v[12:13], v[66:67] op_sel_hi:[1,0]
	v_pk_mul_f32 v[10:11], v[10:11], v[66:67] op_sel_hi:[1,0]
	v_pk_mul_f32 v[8:9], v[8:9], v[66:67] op_sel_hi:[1,0]
	v_pk_mul_f32 v[6:7], v[6:7], v[66:67] op_sel_hi:[1,0]
	v_pk_mul_f32 v[4:5], v[4:5], v[66:67] op_sel_hi:[1,0]
	v_pk_mul_f32 v[2:3], v[2:3], v[66:67] op_sel_hi:[1,0]
	v_pk_mul_f32 v[0:1], v[0:1], v[66:67] op_sel_hi:[1,0]
	v_pk_add_f32 v[66:67], v[98:99], v[172:173]
	v_pk_add_f32 v[68:69], v[68:69], v[70:71]
	v_pk_add_f32 v[70:71], v[96:97], v[170:171]
	v_xor_b32_e32 v64, 0x80000000, v201
	v_pk_add_f32 v[66:67], v[70:71], v[66:67]
	v_mov_b32_e32 v70, v64
	v_pk_add_f32 v[66:67], v[66:67], v[68:69]
	v_mov_b32_e32 v68, v64
	v_pk_add_f32 v[168:169], v[66:67], v[66:67] op_sel:[0,1] op_sel_hi:[1,0]
	v_mov_b32_e32 v66, v64
	v_mov_b32_e32 v169, v65
	v_mov_b32_e32 v65, v64
	v_mov_b32_e32 v67, v64
	v_mov_b32_e32 v69, v64
	v_mov_b32_e32 v71, v64
	v_mov_b32_e32 v72, v64
	v_mov_b32_e32 v73, v64
	v_mov_b32_e32 v74, v64
	v_mov_b32_e32 v75, v64
	v_mov_b32_e32 v76, v64
	v_mov_b32_e32 v77, v64
	v_mov_b32_e32 v78, v64
	v_mov_b32_e32 v79, v64
	v_mov_b32_e32 v80, v64
	v_mov_b32_e32 v81, v64
	v_mov_b32_e32 v82, v64
	v_mov_b32_e32 v83, v64
	v_mov_b32_e32 v84, v64
	v_mov_b32_e32 v85, v64
	v_mov_b32_e32 v86, v64
	v_mov_b32_e32 v87, v64
	v_mov_b32_e32 v88, v64
	v_mov_b32_e32 v89, v64
	v_mov_b32_e32 v90, v64
	v_mov_b32_e32 v91, v64
	v_mov_b32_e32 v92, v64
	v_mov_b32_e32 v93, v64
	v_mov_b32_e32 v94, v64
	v_mov_b32_e32 v95, v64
	v_mov_b32_e32 v174, v96
	v_mov_b32_e32 v210, v170
	v_mov_b32_e32 v212, v98
	v_mov_b32_e32 v214, v172
	v_mov_b32_e32 v175, v160
	v_mov_b32_e32 v211, v162
	v_mov_b32_e32 v213, v164
	v_mov_b32_e32 v215, v166
	v_mov_b32_e32 v160, v97
	v_mov_b32_e32 v162, v171
	v_mov_b32_e32 v164, v99
	v_mov_b32_e32 v166, v173
.LBB0_1133:
	v_cvt_pk_bf16_f32 v96, v174, v210
	v_cvt_pk_bf16_f32 v97, v212, v214
	v_cvt_pk_bf16_f32 v98, v175, v211
	v_cvt_pk_bf16_f32 v99, v213, v215
	s_mov_b64 s[0:1], -1
	s_and_b64 vcc, exec, s[12:13]
	s_waitcnt lgkmcnt(4)
	v_mfma_f32_32x32x16_bf16 v[48:63], v[156:159], v[96:99], v[48:63]
	v_mfma_f32_32x32x16_bf16 v[32:47], v[152:155], v[96:99], v[32:47]
	v_mfma_f32_32x32x16_bf16 v[16:31], v[148:151], v[96:99], v[16:31]
	v_mfma_f32_32x32x16_bf16 v[0:15], v[144:147], v[96:99], v[0:15]
	v_cvt_pk_bf16_f32 v96, v160, v162
	v_cvt_pk_bf16_f32 v97, v164, v166
	v_cvt_pk_bf16_f32 v98, v161, v163
	v_cvt_pk_bf16_f32 v99, v165, v167
	s_nop 1
	s_waitcnt lgkmcnt(0)
	v_mfma_f32_32x32x16_bf16 v[48:63], v[124:127], v[96:99], v[48:63]
	v_mfma_f32_32x32x16_bf16 v[32:47], v[120:123], v[96:99], v[32:47]
	v_mfma_f32_32x32x16_bf16 v[16:31], v[116:119], v[96:99], v[16:31]
	v_mfma_f32_32x32x16_bf16 v[0:15], v[112:115], v[96:99], v[0:15]
	s_cbranch_vccz .LBB0_1135
	s_waitcnt vmcnt(4)
	s_mov_b64 s[0:1], 0

.LBB0_1139:
	v_mov_b64_e32 v[64:65], v[80:81]
	v_mov_b64_e32 v[66:67], v[82:83]
	v_mov_b64_e32 v[68:69], v[84:85]
	v_mov_b64_e32 v[70:71], v[86:87]
	v_mov_b64_e32 v[72:73], v[88:89]
	v_mov_b64_e32 v[74:75], v[90:91]
	v_mov_b64_e32 v[76:77], v[92:93]
	v_mov_b64_e32 v[78:79], v[94:95]
	v_add_u32_e32 v80, v249, v234
	v_add_u32_e32 v81, v249, v235
	ds_read_b128 v[160:163], v80 offset:8192
	ds_read_b128 v[164:167], v81 offset:8192
	v_add_u32_e32 v80, v249, v236
	v_add_u32_e32 v81, v249, v237
	ds_read_b128 v[168:171], v80 offset:8192
	ds_read_b128 v[172:175], v81 offset:8192
	v_add_u32_e32 v80, v248, v239
	ds_read_b128 v[156:159], v80
	ds_read_b128 v[96:99], v80 offset:4096
	ds_read_b128 v[100:103], v80 offset:8192
	ds_read_b128 v[104:107], v80 offset:12288
	v_add_u32_e32 v80, v248, v240
	ds_read_b128 v[108:111], v80
	ds_read_b128 v[144:147], v80 offset:4096
	ds_read_b128 v[148:151], v80 offset:8192
	ds_read_b128 v[152:155], v80 offset:12288
	s_waitcnt lgkmcnt(0)
	v_mfma_f32_32x32x16_bf16 v[80:95], v[160:163], v[128:131], v[64:79]
	v_exp_f32_e32 v160, v112
	v_exp_f32_e32 v162, v113
	v_exp_f32_e32 v161, v120
	v_exp_f32_e32 v163, v121
	v_exp_f32_e32 v202, v119
	v_exp_f32_e32 v203, v127
	v_pk_add_f32 v[204:205], v[160:161], v[162:163]
	v_mfma_f32_32x32x16_bf16 v[80:95], v[164:167], v[132:135], v[80:95]
	v_exp_f32_e32 v164, v114
	v_exp_f32_e32 v166, v115
	v_exp_f32_e32 v165, v122
	v_exp_f32_e32 v167, v123
	s_nop 0
	v_pk_add_f32 v[206:207], v[164:165], v[166:167]
	v_mfma_f32_32x32x16_bf16 v[80:95], v[168:171], v[136:139], v[80:95]
	v_exp_f32_e32 v170, v116
	v_exp_f32_e32 v171, v124
	v_pk_add_f32 v[204:205], v[204:205], v[206:207]
	v_sub_f32_e32 v169, v201, v201
	v_cmp_neq_f32_e64 s[0:1], 0, v169
	v_mfma_f32_32x32x16_bf16 v[80:95], v[172:175], v[140:143], v[80:95]
	v_exp_f32_e32 v172, v117
	v_exp_f32_e32 v174, v118
	v_exp_f32_e32 v173, v125
	v_exp_f32_e32 v175, v126
	v_pk_add_f32 v[206:207], v[170:171], v[172:173]
	v_pk_add_f32 v[208:209], v[174:175], v[202:203]
	s_nop 0
	v_pk_add_f32 v[206:207], v[206:207], v[208:209]
	s_nop 0
	v_pk_add_f32 v[204:205], v[204:205], v[206:207]
	s_nop 0
	v_add_f32_e32 v168, v204, v205
	v_cmp_nge_f32_e32 vcc, s97, v168
	s_or_b64 vcc, s[0:1], vcc
	s_cbranch_vccz .LBB0_1141
	v_max_f32_e32 v64, v113, v113
	v_max_f32_e32 v65, v112, v112
	v_max_f32_e32 v64, v65, v64
	v_max_f32_e32 v65, v115, v115
	v_max_f32_e32 v66, v114, v114
	v_max_f32_e32 v65, v66, v65
	v_max_f32_e32 v66, v119, v119
	v_max_f32_e32 v67, v118, v118
	v_max_f32_e32 v66, v67, v66
	v_max3_f32 v66, v116, v117, v66
	v_max3_f32 v64, v64, v65, v66
	v_max_f32_e32 v65, v123, v123
	v_max_f32_e32 v66, v122, v122
	v_max_f32_e32 v65, v66, v65
	v_max_f32_e32 v66, v127, v127
	v_max_f32_e32 v67, v126, v126
	v_max_f32_e32 v66, v67, v66
	v_max3_f32 v65, v120, v121, v65
	v_max3_f32 v66, v124, v125, v66
	v_max3_f32 v64, v64, v65, v66
	v_add_f32_e32 v64, v169, v64
	ds_bpermute_b32 v65, v244, v64
	s_waitcnt lgkmcnt(0)
	v_max3_f32 v67, v64, v65, 0
	v_sub_f32_e32 v64, v67, v169
	v_sub_f32_e32 v65, v112, v64
	v_exp_f32_e32 v160, v65
	v_sub_f32_e32 v65, v113, v64
	v_exp_f32_e32 v162, v65
	v_sub_f32_e32 v65, v114, v64
	v_exp_f32_e32 v164, v65
	v_sub_f32_e32 v65, v115, v64
	v_exp_f32_e32 v166, v65
	v_sub_f32_e32 v65, v116, v64
	v_exp_f32_e32 v161, v65
	v_sub_f32_e32 v65, v117, v64
	v_exp_f32_e32 v163, v65
	v_sub_f32_e32 v65, v118, v64
	v_exp_f32_e32 v165, v65
	v_sub_f32_e32 v65, v120, v64
	v_exp_f32_e32 v112, v65
	v_sub_f32_e32 v65, v121, v64
	v_exp_f32_e32 v114, v65
	v_sub_f32_e32 v65, v122, v64
	v_exp_f32_e32 v113, v65
	v_sub_f32_e32 v65, v123, v64
	v_exp_f32_e32 v115, v65
	v_sub_f32_e32 v65, v124, v64
	v_exp_f32_e32 v116, v65
	v_sub_f32_e32 v65, v125, v64
	v_exp_f32_e32 v120, v65
	v_sub_f32_e32 v65, v126, v64
	v_exp_f32_e32 v117, v65
	v_sub_f32_e32 v65, v127, v64
	v_exp_f32_e32 v121, v65
	v_sub_f32_e32 v64, v119, v64
	v_exp_f32_e64 v66, -v67
	v_exp_f32_e32 v167, v64
	v_pk_add_f32 v[64:65], v[112:113], v[114:115]
	v_pk_add_f32 v[68:69], v[116:117], v[120:121]
	v_pk_add_f32 v[64:65], v[64:65], v[64:65] op_sel:[0,1] op_sel_hi:[1,0]
	v_pk_add_f32 v[68:69], v[68:69], v[68:69] op_sel:[0,1] op_sel_hi:[1,0]
	v_mov_b32_e32 v65, v201
	v_mov_b32_e32 v69, v67
	v_mul_f32_e32 v177, v177, v66
	v_pk_add_f32 v[118:119], v[64:65], v[68:69]
	v_pk_mul_f32 v[62:63], v[62:63], v[66:67] op_sel_hi:[1,0]
	v_pk_mul_f32 v[60:61], v[60:61], v[66:67] op_sel_hi:[1,0]
	v_pk_mul_f32 v[58:59], v[58:59], v[66:67] op_sel_hi:[1,0]
	v_pk_mul_f32 v[56:57], v[56:57], v[66:67] op_sel_hi:[1,0]
	v_pk_mul_f32 v[54:55], v[54:55], v[66:67] op_sel_hi:[1,0]
	v_pk_mul_f32 v[52:53], v[52:53], v[66:67] op_sel_hi:[1,0]
	v_pk_mul_f32 v[50:51], v[50:51], v[66:67] op_sel_hi:[1,0]
	v_pk_mul_f32 v[48:49], v[48:49], v[66:67] op_sel_hi:[1,0]
	v_pk_mul_f32 v[46:47], v[46:47], v[66:67] op_sel_hi:[1,0]
	v_pk_mul_f32 v[44:45], v[44:45], v[66:67] op_sel_hi:[1,0]
	v_pk_mul_f32 v[42:43], v[42:43], v[66:67] op_sel_hi:[1,0]
	v_pk_mul_f32 v[40:41], v[40:41], v[66:67] op_sel_hi:[1,0]
	v_pk_mul_f32 v[38:39], v[38:39], v[66:67] op_sel_hi:[1,0]
	v_pk_mul_f32 v[36:37], v[36:37], v[66:67] op_sel_hi:[1,0]
	v_pk_mul_f32 v[34:35], v[34:35], v[66:67] op_sel_hi:[1,0]
	v_pk_mul_f32 v[32:33], v[32:33], v[66:67] op_sel_hi:[1,0]
	v_pk_mul_f32 v[30:31], v[30:31], v[66:67] op_sel_hi:[1,0]
	v_pk_mul_f32 v[28:29], v[28:29], v[66:67] op_sel_hi:[1,0]
	v_pk_mul_f32 v[26:27], v[26:27], v[66:67] op_sel_hi:[1,0]
	v_pk_mul_f32 v[24:25], v[24:25], v[66:67] op_sel_hi:[1,0]
	v_pk_mul_f32 v[22:23], v[22:23], v[66:67] op_sel_hi:[1,0]
	v_pk_mul_f32 v[20:21], v[20:21], v[66:67] op_sel_hi:[1,0]
	v_pk_mul_f32 v[18:19], v[18:19], v[66:67] op_sel_hi:[1,0]
	v_pk_mul_f32 v[16:17], v[16:17], v[66:67] op_sel_hi:[1,0]
	v_pk_mul_f32 v[14:15], v[14:15], v[66:67] op_sel_hi:[1,0]
	v_pk_mul_f32 v[12:13], v[12:13], v[66:67] op_sel_hi:[1,0]
	v_pk_mul_f32 v[10:11], v[10:11], v[66:67] op_sel_hi:[1,0]
	v_pk_mul_f32 v[8:9], v[8:9], v[66:67] op_sel_hi:[1,0]
	v_pk_mul_f32 v[6:7], v[6:7], v[66:67] op_sel_hi:[1,0]
	v_pk_mul_f32 v[4:5], v[4:5], v[66:67] op_sel_hi:[1,0]
	v_pk_mul_f32 v[2:3], v[2:3], v[66:67] op_sel_hi:[1,0]
	v_pk_mul_f32 v[0:1], v[0:1], v[66:67] op_sel_hi:[1,0]
	v_pk_add_f32 v[66:67], v[164:165], v[166:167]
	v_pk_add_f32 v[68:69], v[160:161], v[162:163]
	v_xor_b32_e32 v64, 0x80000000, v119
	v_pk_add_f32 v[66:67], v[68:69], v[66:67]
	v_mov_b32_e32 v65, v64
	v_pk_add_f32 v[66:67], v[66:67], v[66:67] op_sel:[0,1] op_sel_hi:[1,0]
	v_mov_b32_e32 v68, v64
	v_mov_b32_e32 v67, v201
	v_pk_add_f32 v[168:169], v[66:67], v[118:119] neg_lo:[0,1] neg_hi:[0,1]
	v_mov_b32_e32 v67, v64
	v_add_f32_e32 v168, v66, v118
	v_mov_b32_e32 v66, v64
	v_mov_b32_e32 v69, v64
	v_mov_b32_e32 v70, v64
	v_mov_b32_e32 v71, v64
	v_mov_b32_e32 v72, v64
	v_mov_b32_e32 v73, v64
	v_mov_b32_e32 v74, v64
	v_mov_b32_e32 v75, v64
	v_mov_b32_e32 v76, v64
	v_mov_b32_e32 v77, v64
	v_mov_b32_e32 v78, v64
	v_mov_b32_e32 v79, v64
	v_mov_b32_e32 v201, v119
	v_mov_b32_e32 v170, v161
	v_mov_b32_e32 v172, v163
	v_mov_b32_e32 v174, v165
	v_mov_b32_e32 v202, v167
	v_mov_b32_e32 v161, v112
	v_mov_b32_e32 v163, v114
	v_mov_b32_e32 v165, v113
	v_mov_b32_e32 v167, v115
	v_mov_b32_e32 v171, v116
	v_mov_b32_e32 v173, v120
	v_mov_b32_e32 v175, v117
	v_mov_b32_e32 v203, v121
